# shadow-GEMM rebalance: 48 tiles of group 1's ZO GEMM computed in the idle third-round slots of the ZO(0) phase, later shadow ranges shifted
# baseline (speedup 1.0000x reference)
.LBB0_300:
	s_cmp_lt_i32 s33, 4
	s_cbranch_scc1 .LBB0_305
	s_cmp_eq_u32 s33, 4
	s_mov_b64 s[8:9], 0
	s_cbranch_scc0 .LBB0_306
	s_cmp_lg_u32 s76, 0
	s_cselect_b64 s[10:11], -1, 0
	s_cmp_lg_u64 s[10:11], 0
	v_readlane_b32 s0, v254, 45
	s_addc_u32 s18, s0, 0
	s_or_b32 s0, s61, s76
	s_cmp_eq_u32 s0, 0
	s_cbranch_scc1 .LBB0_307
	s_cmp_lt_u32 s18, 4
	s_cselect_b64 s[0:1], -1, 0
	s_and_b64 s[4:5], s[10:11], s[0:1]
	s_and_b64 vcc, exec, s[4:5]
	s_cbranch_vccz .LBB0_308
	s_cmp_lg_u32 s61, 0
	s_cbranch_scc1 .Lz1_std
	s_cmp_eq_u32 s76, 1
	s_cbranch_scc0 .Lz1_std
	s_waitcnt lgkmcnt(0)
	s_mov_b64 s[12:13], -1
	s_branch .LBB0_325
.Lz1_std:
	s_cmp_eq_u32 s76, 1
	v_readlane_b32 s4, v254, 55
	s_cselect_b64 s[0:1], -1, 0
	v_readlane_b32 s5, v254, 56
	s_and_b64 s[0:1], s[4:5], s[0:1]
	v_readlane_b32 s4, v254, 61
	v_readlane_b32 s5, v254, 62
	s_nor_b64 s[4:5], s[4:5], s[0:1]
	s_waitcnt lgkmcnt(0)
	s_mov_b64 s[12:13], -1
	s_andn2_b64 vcc, exec, s[4:5]
	s_cbranch_vccnz .LBB0_325
	s_branch .LBB0_309

.LBB0_325:
	s_mov_b32 s22, 0
	s_and_b64 vcc, exec, s[12:13]
	v_mov_b32_e32 v1, s19
	s_mov_b32 s13, s54
	s_mov_b32 s12, 0
	s_cbranch_vccz .LBB0_334
	s_mul_i32 s0, s18, 0x1200000
	s_add_u32 s4, s0, 0x3998100
	s_bitcmp1_b32 s18, 0
	s_mov_b32 s0, 0x16b98100
	s_cselect_b32 s5, s0, 0x11198100
	s_andn2_b64 vcc, exec, s[10:11]
	s_mov_b32 s0, 0
	s_cbranch_vccnz .LBB0_329
	s_cmp_lg_u32 s61, 0
	s_cbranch_scc1 .Lz1_a
	s_mov_b32 s12, 0
	s_movk_i32 s17, 48
	s_movk_i32 s22, 0xd0
	s_movk_i32 s13, 48
	s_branch .LBB0_331
.Lz1_a:
	v_readlane_b32 s6, v254, 59
	v_readlane_b32 s7, v254, 60
	s_andn2_b64 vcc, exec, s[6:7]
	s_cbranch_vccnz .LBB0_330
	s_cmp_eq_u32 s76, 1
	v_readlane_b32 s1, v255, 2
	v_readlane_b32 s3, v255, 3
	s_cselect_b32 s12, s1, s3
	s_mul_i32 s1, s23, 20
	s_cselect_b32 s17, s3, s1
	v_readlane_b32 s1, v253, 16
	s_cselect_b32 s22, 0x90, 0
	s_cselect_b32 s13, s1, s54
	s_cmp_lg_u32 s18, 1
	s_cbranch_scc1 .LBB0_331
	s_add_i32 s12, s12, 48
	s_add_i32 s17, s17, 48
	s_mul_i32 s1, s23, 20
	s_min_u32 s17, s17, s1
	s_min_u32 s12, s12, s1
	s_branch .LBB0_331

.LBB0_330:
	s_movk_i32 s22, 0x90
	v_readlane_b32 s17, v255, 2
	v_readlane_b32 s13, v253, 16
	s_cmp_lg_u32 s18, 1
	s_cbranch_scc1 .LBB0_331
	s_movk_i32 s12, 48
	s_add_i32 s17, s17, 48
